# v47 plus copy+canonicalise v_max folds extended to the peeled first attention tile (28 more)
# speedup vs baseline: 1.0025x; 1.0025x over previous
; #define LAS __attribute__((address_space(3)))
; DI float shx16(float v) { return __int_as_float(__builtin_amdgcn_ds_swizzle(__float_as_int(v), 0x401F)); }
; DI float fast_exp2(float x) { return __builtin_amdgcn_exp2f(x); }
; DI void attn_item(const Params& p, int layer, int b, int hh, int jq, lchar* sm, float lam, float oml, int tid, int w) {
;     ...
;       bf16x8 pb[2][2];
; #pragma unroll
;       for (int m = 0; m < 2; ++m) {
;         float mx = fmaxf(fmaxf(S[m][0][0], S[m][0][1]), fmaxf(S[m][0][2], S[m][0][3]));
; #pragma unroll
;         for (int k16 = 1; k16 < 4; ++k16) mx = fmaxf(fmaxf(mx, fmaxf(S[m][k16][0], S[m][k16][1])), fmaxf(S[m][k16][2], S[m][k16][3]));
;         mx = fmaxf(mx, shx16(mx));
;         mx = fmaxf(mx, shx32(mx, idx32));
;         if (kt == 0 || __builtin_amdgcn_ballot_w64(mx > 8.0f) != 0ull) {
;           const float dlt = kt == 0 ? mx : fmaxf(mx, 0.f);
;           const float alpha = fast_exp2(-dlt);
;           mrun[m] += dlt;
; #pragma unroll
;           for (int dt = 0; dt < 8; ++dt) { O[m][dt][0] *= alpha; O[m][dt][1] *= alpha; O[m][dt][2] *= alpha; O[m][dt][3] *= alpha; }
;           Osum[m][0] *= alpha; Osum[m][1] *= alpha; Osum[m][2] *= alpha; Osum[m][3] *= alpha;
; #pragma unroll
;           for (int k16 = 0; k16 < 4; ++k16)
; #pragma unroll
;             for (int r = 0; r < 4; ++r) S[m][k16][r] -= dlt;
;         }
; #pragma unroll
;         for (int k16 = 0; k16 < 4; ++k16)
; #pragma unroll
;           for (int r = 0; r < 4; ++r) S[m][k16][r] = fast_exp2(S[m][k16][r]);
; #pragma unroll
;         for (int kk = 0; kk < 2; ++kk) {
;           u32x4 t;
;           t[0] = pack2(S[m][2 * kk][0], S[m][2 * kk][1]); t[1] = pack2(S[m][2 * kk][2], S[m][2 * kk][3]);
;           t[2] = pack2(S[m][2 * kk + 1][0], S[m][2 * kk + 1][1]); t[3] = pack2(S[m][2 * kk + 1][2], S[m][2 * kk + 1][3]);
;           pb[m][kk] = __builtin_bit_cast(bf16x8, t);
;           Osum[m] = mfma16(ones, pb[m][kk], Osum[m]);
;         }
;       }
; #pragma unroll
;       for (int kk = 0; kk < 2; ++kk) {
;         bf16x8 vf[8];
; #pragma unroll
;         for (int dt = 0; dt < 8; ++dt) vf[dt] = *(const LAS bf16x8*)(vb + dt * 2048 + voff[kk]);
;         SCHED;
; #pragma unroll
;         for (int dt = 0; dt < 8; ++dt) {
;           O[0][dt] = mfma16(vf[dt], pb[0][kk], O[0][dt]);
;           O[1][dt] = mfma16(vf[dt], pb[1][kk], O[1][dt]);
;         }
;       }
.LBB0_166:
	s_nop 2
	v_max_f32_e32 v44, v22, v23
	v_max_f32_e32 v45, v40, v41
	v_max3_f32 v44, v20, v21, v44
	v_max_f32_e32 v46, v42, v43
	v_max3_f32 v44, v44, v45, v46
	v_max_f32_e32 v45, v48, v49
	v_max_f32_e32 v46, v50, v51
	v_max3_f32 v44, v44, v45, v46
	v_max_f32_e32 v45, v52, v53
	v_max_f32_e32 v47, v54, v54
	v_max_f32_e32 v46, v47, v55
	v_max3_f32 v44, v44, v45, v46
	ds_swizzle_b32 v45, v44 offset:swizzle(SWAP,16)
	v_add_u32_e32 v68, 0, v153
	s_or_b32 s37, s63, 15
	s_waitcnt lgkmcnt(0)
	v_max_f32_e32 v44, v44, v45
	ds_bpermute_b32 v45, v150, v44
	s_waitcnt lgkmcnt(0)
	v_max_f32_e32 v57, v44, v45
	v_sub_f32_e32 v48, v48, v57
	v_sub_f32_e32 v49, v49, v57
	v_sub_f32_e32 v50, v50, v57
	v_sub_f32_e32 v51, v51, v57
	v_exp_f32_e32 v48, v48
	v_exp_f32_e32 v49, v49
	v_exp_f32_e32 v50, v50
	v_exp_f32_e32 v51, v51
	v_sub_f32_e32 v40, v40, v57
	v_cvt_pk_bf16_f32 v92, v48, v49
	v_cvt_pk_bf16_f32 v93, v50, v51
	v_max_f32_e32 v48, v26, v27
	v_max_f32_e32 v49, v28, v29
	v_max3_f32 v48, v24, v25, v48
	v_max_f32_e32 v50, v30, v31
	v_max3_f32 v48, v48, v49, v50
	v_max_f32_e32 v49, v32, v33
	v_max_f32_e32 v50, v34, v35
	v_max3_f32 v48, v48, v49, v50
	v_max_f32_e32 v49, v36, v37
	v_max_f32_e32 v50, v38, v39
	v_max3_f32 v48, v48, v49, v50
	ds_swizzle_b32 v49, v48 offset:swizzle(SWAP,16)
	v_sub_f32_e32 v41, v41, v57
	v_exp_f32_e32 v56, v40
	v_exp_f32_e32 v58, v41
	v_sub_f32_e32 v52, v52, v57
	s_waitcnt lgkmcnt(0)
	v_max_f32_e32 v48, v48, v49
	ds_bpermute_b32 v49, v150, v48
	v_sub_f32_e32 v53, v53, v57
	v_sub_f32_e32 v54, v54, v57
	v_sub_f32_e32 v55, v55, v57
	v_exp_f32_e32 v52, v52
	v_exp_f32_e32 v53, v53
	v_exp_f32_e32 v54, v54
	v_exp_f32_e32 v55, v55
	v_sub_f32_e32 v42, v42, v57
	s_waitcnt lgkmcnt(0)
	v_exp_f32_e32 v59, v42
	v_cvt_pk_bf16_f32 v42, v56, v58
	v_max_f32_e32 v56, v48, v49
	v_sub_f32_e32 v28, v28, v56
	v_sub_f32_e32 v29, v29, v56
	v_sub_f32_e32 v30, v30, v56
	v_sub_f32_e32 v31, v31, v56
	v_sub_f32_e32 v48, v24, v56
	v_sub_f32_e32 v49, v25, v56
	v_sub_f32_e32 v50, v26, v56
	v_sub_f32_e32 v51, v27, v56
	v_exp_f32_e64 v24, -v56
	v_cvt_pk_bf16_f32 v94, v52, v53
	v_cvt_pk_bf16_f32 v95, v54, v55
	v_exp_f32_e32 v48, v48
	v_exp_f32_e32 v49, v49
	v_exp_f32_e32 v50, v50
	v_exp_f32_e32 v51, v51
	v_exp_f32_e32 v52, v28
	v_exp_f32_e32 v53, v29
	v_exp_f32_e32 v54, v30
	v_exp_f32_e32 v31, v31
	v_sub_f32_e32 v36, v36, v56
	v_sub_f32_e32 v37, v37, v56
	v_sub_f32_e32 v38, v38, v56
	v_sub_f32_e32 v39, v39, v56
	v_sub_f32_e32 v32, v32, v56
	v_sub_f32_e32 v33, v33, v56
	v_sub_f32_e32 v34, v34, v56
	v_sub_f32_e32 v35, v35, v56
	v_mul_f32_e32 v24, 0, v24
	v_exp_f32_e64 v44, -v57
	v_sub_f32_e32 v43, v43, v57
	v_sub_f32_e32 v20, v20, v57
	v_sub_f32_e32 v21, v21, v57
	v_sub_f32_e32 v22, v22, v57
	v_sub_f32_e32 v23, v23, v57
	v_mov_b32_e32 v25, v24
	v_mov_b32_e32 v26, v24
	v_mov_b32_e32 v27, v24
	v_pk_add_f32 v[140:141], v[56:57], 0 op_sel_hi:[1,0]
	v_exp_f32_e32 v55, v32
	v_exp_f32_e32 v56, v33
	v_exp_f32_e32 v57, v34
	v_exp_f32_e32 v58, v35
	v_exp_f32_e32 v36, v36
	v_exp_f32_e32 v37, v37
	v_exp_f32_e32 v38, v38
	v_exp_f32_e32 v39, v39
	v_cvt_pk_bf16_f32 v28, v48, v49
	v_cvt_pk_bf16_f32 v29, v50, v51
	v_cvt_pk_bf16_f32 v30, v52, v53
	v_cvt_pk_bf16_f32 v31, v54, v31
	v_exp_f32_e32 v43, v43
	v_exp_f32_e32 v20, v20
	v_mfma_f32_16x16x32_bf16 v[32:35], v[0:3], v[28:31], v[24:27]
	v_exp_f32_e32 v21, v21
	v_exp_f32_e32 v22, v22
	v_exp_f32_e32 v23, v23
	v_cvt_pk_bf16_f32 v96, v55, v56
	v_cvt_pk_bf16_f32 v97, v57, v58
	v_cvt_pk_bf16_f32 v98, v36, v37
	v_cvt_pk_bf16_f32 v99, v38, v39
	v_cvt_pk_bf16_f32 v43, v59, v43
	v_mul_f32_e32 v44, 0, v44
	v_mfma_f32_16x16x32_bf16 v[88:91], v[0:3], v[96:99], v[32:35]
	s_nop 2
	ds_read_b128 v[32:35], v68 offset:16384
	ds_read_b128 v[36:39], v68 offset:18432
	ds_read_b128 v[48:51], v68 offset:20480
	ds_read_b128 v[52:55], v68 offset:22528
	ds_read_b128 v[56:59], v68 offset:24576
	ds_read_b128 v[60:63], v68 offset:26624
	ds_read_b128 v[64:67], v68 offset:28672
	ds_read_b128 v[68:71], v68 offset:30720
	v_mov_b32_e32 v45, v44
	v_mov_b32_e32 v46, v44
	v_mov_b32_e32 v47, v44
	v_cvt_pk_bf16_f32 v40, v20, v21
	v_cvt_pk_bf16_f32 v41, v22, v23
	s_nop 1
	v_mfma_f32_16x16x32_bf16 v[20:23], v[0:3], v[40:43], v[44:47]
	v_mfma_f32_16x16x32_bf16 v[20:23], v[0:3], v[92:95], v[20:23]
	s_waitcnt lgkmcnt(0)
	v_mfma_f32_16x16x32_bf16 v[108:111], v[56:59], v[40:43], v[44:47]
	v_mfma_f32_16x16x32_bf16 v[112:115], v[56:59], v[28:31], v[24:27]
	v_add_u32_e32 v56, 0, v154
	v_mfma_f32_16x16x32_bf16 v[72:75], v[32:35], v[40:43], v[44:47]
	v_mfma_f32_16x16x32_bf16 v[32:35], v[32:35], v[28:31], v[24:27]
	v_mfma_f32_16x16x32_bf16 v[76:79], v[36:39], v[40:43], v[44:47]
	v_mfma_f32_16x16x32_bf16 v[36:39], v[36:39], v[28:31], v[24:27]
	v_mfma_f32_16x16x32_bf16 v[100:103], v[48:51], v[40:43], v[44:47]
	v_mfma_f32_16x16x32_bf16 v[48:51], v[48:51], v[28:31], v[24:27]
	v_mfma_f32_16x16x32_bf16 v[104:107], v[52:55], v[40:43], v[44:47]
	v_mfma_f32_16x16x32_bf16 v[52:55], v[52:55], v[28:31], v[24:27]
	v_mfma_f32_16x16x32_bf16 v[116:119], v[60:63], v[40:43], v[44:47]
	v_mfma_f32_16x16x32_bf16 v[120:123], v[60:63], v[28:31], v[24:27]
	v_mfma_f32_16x16x32_bf16 v[164:167], v[64:67], v[40:43], v[44:47]
	v_mfma_f32_16x16x32_bf16 v[168:171], v[64:67], v[28:31], v[24:27]
	v_mfma_f32_16x16x32_bf16 v[172:175], v[68:71], v[40:43], v[44:47]
	v_mfma_f32_16x16x32_bf16 v[28:31], v[68:71], v[28:31], v[24:27]
	s_nop 2
	ds_read_b128 v[24:27], v56 offset:16384
	ds_read_b128 v[40:43], v56 offset:18432
	ds_read_b128 v[44:47], v56 offset:20480
	ds_read_b128 v[60:63], v56 offset:22528
	ds_read_b128 v[178:181], v56 offset:24576
	ds_read_b128 v[182:185], v56 offset:26624
	ds_read_b128 v[186:189], v56 offset:28672
	ds_read_b128 v[190:193], v56 offset:30720
	s_waitcnt lgkmcnt(0)
	v_mfma_f32_16x16x32_bf16 v[80:83], v[24:27], v[92:95], v[72:75]
	s_lshl_b32 s28, s41, 7
	s_addk_i32 s63, 0xff50
	s_mov_b32 s41, 1
	v_mfma_f32_16x16x32_bf16 v[84:87], v[24:27], v[96:99], v[32:35]
	s_mov_b32 s44, 0x18000
	s_mov_b32 s72, 64
	v_mfma_f32_16x16x32_bf16 v[72:75], v[40:43], v[92:95], v[76:79]
	v_mfma_f32_16x16x32_bf16 v[76:79], v[40:43], v[96:99], v[36:39]
	v_mfma_f32_16x16x32_bf16 v[64:67], v[44:47], v[92:95], v[100:103]
	v_mfma_f32_16x16x32_bf16 v[68:71], v[44:47], v[96:99], v[48:51]
	v_mfma_f32_16x16x32_bf16 v[56:59], v[60:63], v[92:95], v[104:107]
	v_mfma_f32_16x16x32_bf16 v[60:63], v[60:63], v[96:99], v[52:55]
	v_mfma_f32_16x16x32_bf16 v[48:51], v[178:181], v[92:95], v[108:111]
	v_mfma_f32_16x16x32_bf16 v[52:55], v[178:181], v[96:99], v[112:115]
	v_mfma_f32_16x16x32_bf16 v[40:43], v[182:185], v[92:95], v[116:119]
	v_mfma_f32_16x16x32_bf16 v[44:47], v[182:185], v[96:99], v[120:123]
	v_mfma_f32_16x16x32_bf16 v[36:39], v[186:189], v[92:95], v[164:167]
	v_mfma_f32_16x16x32_bf16 v[32:35], v[186:189], v[96:99], v[168:171]
	s_nop 1
	v_subrev_u32_e32 v164, s28, v162
	v_mfma_f32_16x16x32_bf16 v[24:27], v[190:193], v[92:95], v[172:175]
	v_mfma_f32_16x16x32_bf16 v[28:31], v[190:193], v[96:99], v[28:31]
	s_branch .LBB0_169

; DI void gemm256_tile(const Params& p, int mode, int layer, const u16* R, const u16* Cc, int brow, int bcol, lchar* shm, int tid_in, int wid) {
;     ...
;     if (kh == 0) {
; #pragma unroll
;       for (int j = 0; j < 16; ++j) { LL[tok * 32 + ((j + tok) & 31)] = __float_as_uint(L0[j]); LL[tok * 32 + ((16 + j + tok) & 31)] = __float_as_uint(L1[j]); }
;       float s1[16], s2[16], v[16];
; #pragma unroll
;       for (int j = 0; j < 16; ++j) { s1[j] = __uint_as_float(__float_as_uint(L0[j]) & ~127u); s2[j] = __uint_as_float(__float_as_uint(L1[j]) & ~127u); v[j] = -3.0e38f; }
; #pragma unroll
;       for (int ch = 0; ch < 4; ++ch) {
;         float wk[16];
; #pragma unroll
;         for (int i = 0; i < 16; ++i) {
;           constexpr unsigned char PAIRS[64] = {0, 1, 2, 3, 4, 5, 6, 7, 8, 9, 10, 11, 12, 13, 14, 15, 16, 17, 18, 19, 20, 21, 22, 23, 32, 33, 34, 35, 36, 48, 49, 50, 51, 64, 65, 66, 80, 81, 96, 97, 112, 113, 128, 144, 160, 176, 192, 208, 224, 240, 255, 255, 255, 255, 255, 255, 255, 255, 255, 255, 255, 255, 255, 255};
;           const int code = PAIRS[ch * 16 + i];
;           if (code == 255) { wk[i] = -3.0e38f; }
;           else { const float sm = s1[code >> 4] + s2[code & 15]; wk[i] = __uint_as_float((__float_as_uint(sm) & ~255u) | (unsigned)code); }
.LBB0_235:
	s_and_b64 vcc, exec, s[90:91]
	s_barrier
	s_cbranch_vccz .LBB0_237
	v_mad_u32_u24 v165, v164, 48, v166
	v_and_b32_e32 v167, 31, v163
	v_lshl_add_u32 v167, v167, 2, v165
	ds_write_b32 v167, v140
	v_bitop3_b32 v167, v163, 31, 16 bitop3:0x48
	v_lshl_add_u32 v167, v167, 2, v165
	ds_write_b32 v167, v156
	v_add_u32_e32 v167, 1, v163
	v_and_b32_e32 v167, 31, v167
	v_xor_b32_e32 v166, 16, v163
	v_lshl_add_u32 v167, v167, 2, v165
	ds_write_b32 v167, v141
	v_add_u32_e32 v167, 1, v166
	v_and_b32_e32 v167, 31, v167
	v_lshl_add_u32 v167, v167, 2, v165
	ds_write_b32 v167, v157
	v_add_u32_e32 v167, 2, v163
	v_and_b32_e32 v167, 31, v167
	v_lshl_add_u32 v167, v167, 2, v165
	ds_write_b32 v167, v142
	v_add_u32_e32 v167, 2, v166
	v_and_b32_e32 v167, 31, v167
	v_lshl_add_u32 v167, v167, 2, v165
	ds_write_b32 v167, v158
	v_add_u32_e32 v167, 3, v163
	v_and_b32_e32 v167, 31, v167
	v_lshl_add_u32 v167, v167, 2, v165
	ds_write_b32 v167, v143
	v_add_u32_e32 v167, 3, v166
	v_and_b32_e32 v167, 31, v167
	v_lshl_add_u32 v167, v167, 2, v165
	ds_write_b32 v167, v159
	v_add_u32_e32 v167, 4, v163
	v_and_b32_e32 v167, 31, v167
	v_lshl_add_u32 v167, v167, 2, v165
	ds_write_b32 v167, v136
	v_add_u32_e32 v167, 4, v166
	v_and_b32_e32 v167, 31, v167
	v_lshl_add_u32 v167, v167, 2, v165
	ds_write_b32 v167, v152
	v_add_u32_e32 v167, 5, v163
	v_and_b32_e32 v167, 31, v167
	v_lshl_add_u32 v167, v167, 2, v165
	ds_write_b32 v167, v137
	v_add_u32_e32 v167, 5, v166
	v_and_b32_e32 v167, 31, v167
	v_lshl_add_u32 v167, v167, 2, v165
	ds_write_b32 v167, v153
	v_add_u32_e32 v167, 6, v163
	v_and_b32_e32 v167, 31, v167
	v_lshl_add_u32 v167, v167, 2, v165
	ds_write_b32 v167, v138
	v_add_u32_e32 v167, 6, v166
	v_and_b32_e32 v167, 31, v167
	v_lshl_add_u32 v167, v167, 2, v165
	ds_write_b32 v167, v154
	v_add_u32_e32 v167, 7, v163
	v_and_b32_e32 v167, 31, v167
	v_lshl_add_u32 v167, v167, 2, v165
	ds_write_b32 v167, v139
	v_add_u32_e32 v167, 7, v166
	v_and_b32_e32 v167, 31, v167
	v_lshl_add_u32 v167, v167, 2, v165
	ds_write_b32 v167, v155
	v_add_u32_e32 v167, 8, v163
	v_and_b32_e32 v167, 31, v167
	v_lshl_add_u32 v167, v167, 2, v165
	ds_write_b32 v167, v132
	v_add_u32_e32 v167, 8, v166
	v_and_b32_e32 v167, 31, v167
	v_lshl_add_u32 v167, v167, 2, v165
	ds_write_b32 v167, v148
	v_add_u32_e32 v167, 9, v163
	v_and_b32_e32 v167, 31, v167
	v_lshl_add_u32 v167, v167, 2, v165
	ds_write_b32 v167, v133
	v_add_u32_e32 v167, 9, v166
	v_and_b32_e32 v167, 31, v167
	v_lshl_add_u32 v167, v167, 2, v165
	ds_write_b32 v167, v149
	v_add_u32_e32 v167, 10, v163
	v_and_b32_e32 v167, 31, v167
	v_lshl_add_u32 v167, v167, 2, v165
	ds_write_b32 v167, v134
	v_add_u32_e32 v167, 10, v166
	v_and_b32_e32 v167, 31, v167
	v_lshl_add_u32 v167, v167, 2, v165
	ds_write_b32 v167, v150
	v_add_u32_e32 v167, 11, v163
	v_and_b32_e32 v167, 31, v167
	v_lshl_add_u32 v167, v167, 2, v165
	ds_write_b32 v167, v135
	v_add_u32_e32 v167, 11, v166
	v_and_b32_e32 v167, 31, v167
	v_lshl_add_u32 v167, v167, 2, v165
	ds_write_b32 v167, v151
	v_add_u32_e32 v167, 12, v163
	v_and_b32_e32 v167, 31, v167
	v_lshl_add_u32 v167, v167, 2, v165
	ds_write_b32 v167, v128
	v_add_u32_e32 v167, 12, v166
	v_and_b32_e32 v167, 31, v167
	v_lshl_add_u32 v167, v167, 2, v165
	ds_write_b32 v167, v144
	v_add_u32_e32 v167, 13, v163
	v_and_b32_e32 v167, 31, v167
	v_lshl_add_u32 v167, v167, 2, v165
	ds_write_b32 v167, v129
	v_add_u32_e32 v167, 13, v166
	v_and_b32_e32 v167, 31, v167
	v_lshl_add_u32 v167, v167, 2, v165
	ds_write_b32 v167, v145
	v_add_u32_e32 v167, 14, v163
	v_and_b32_e32 v167, 31, v167
	v_lshl_add_u32 v167, v167, 2, v165
	ds_write_b32 v167, v130
	v_add_u32_e32 v167, 14, v166
	v_and_b32_e32 v167, 31, v167
	v_lshl_add_u32 v167, v167, 2, v165
	ds_write_b32 v167, v146
	v_add_u32_e32 v167, 15, v163
	v_add_u32_e32 v166, 15, v166
	v_and_b32_e32 v167, 31, v167
	v_and_b32_e32 v166, 31, v166
	v_lshl_add_u32 v167, v167, 2, v165
	v_lshl_add_u32 v166, v166, 2, v165
	ds_write_b32 v167, v131
	ds_write_b32 v166, v147
	v_and_b32_e32 v166, 0xffffff80, v140
	v_and_b32_e32 v140, 0xffffff80, v156
	v_and_b32_e32 v141, 0xffffff80, v141
	v_and_b32_e32 v156, 0xffffff80, v157
	v_and_b32_e32 v157, 0xffffff80, v158
	v_and_b32_e32 v158, 0xffffff80, v159
	v_and_b32_e32 v152, 0xffffff80, v152
	v_and_b32_e32 v153, 0xffffff80, v153
	v_and_b32_e32 v154, 0xffffff80, v154
	v_and_b32_e32 v155, 0xffffff80, v155
	v_and_b32_e32 v148, 0xffffff80, v148
	v_and_b32_e32 v149, 0xffffff80, v149
	v_and_b32_e32 v150, 0xffffff80, v150
	v_and_b32_e32 v151, 0xffffff80, v151
	v_and_b32_e32 v159, 0xffffff80, v128
	v_and_b32_e32 v144, 0xffffff80, v144
	v_and_b32_e32 v167, 0xffffff80, v129
	v_and_b32_e32 v145, 0xffffff80, v145
	v_and_b32_e32 v129, 0xffffff80, v130
	v_and_b32_e32 v130, 0xffffff80, v146
	v_and_b32_e32 v128, 0xffffff80, v131
	v_and_b32_e32 v131, 0xffffff80, v147
	v_add_f32_e32 v146, v166, v140
	v_add_f32_e32 v147, v166, v156
	v_add_f32_e32 v168, v166, v157
	v_add_f32_e32 v169, v166, v158
	v_add_f32_e32 v170, v166, v152
	v_add_f32_e32 v171, v166, v153
	v_add_f32_e32 v172, v166, v154
	v_add_f32_e32 v173, v166, v155
	v_add_f32_e32 v148, v166, v148
	v_add_f32_e32 v149, v166, v149
	v_add_f32_e32 v150, v166, v150
	v_add_f32_e32 v151, v166, v151
	v_add_f32_e32 v144, v166, v144
	v_add_f32_e32 v145, v166, v145
	v_add_f32_e32 v130, v166, v130
	v_add_f32_e32 v131, v166, v131
	v_add_f32_e32 v166, v141, v140
	v_add_f32_e32 v174, v141, v156
	v_and_or_b32 v166, v166, s87, 16
	v_and_or_b32 v174, v174, s87, 17
	v_add_f32_e32 v175, v141, v157
	v_add_f32_e32 v176, v141, v158
	v_and_b32_e32 v142, 0xffffff80, v142
	v_and_or_b32 v175, v175, s87, 18
	v_and_or_b32 v176, v176, s87, 19
	v_add_f32_e32 v178, v141, v152
; DI void ce_desc(float& hi, float& lo) { const float a = hi, b = lo; hi = fmaxf(a, b); lo = fminf(a, b); }
; DI void bitonic_sort16(float (&v)[16]) {
; #pragma unroll
;   for (int k = 2; k <= 16; k <<= 1)
; #pragma unroll
;     for (int j = k >> 1; j > 0; j >>= 1)
; #pragma unroll
;       for (int i = 0; i < 16; ++i) {
;         const int l = i ^ j;
;         if (l > i) { if ((i & k) == 0 || k == 16) ce_desc(v[i], v[l]); else ce_desc(v[l], v[i]); }
;       }
; }
; DI void gemm256_tile(const Params& p, int mode, int layer, const u16* R, const u16* Cc, int brow, int bcol, lchar* shm, int tid_in, int wid) {
;     ...
; #pragma unroll
;       for (int ch = 0; ch < 4; ++ch) {
;         float wk[16];
; #pragma unroll
;         for (int i = 0; i < 16; ++i) {
;           constexpr unsigned char PAIRS[64] = {0, 1, 2, 3, 4, 5, 6, 7, 8, 9, 10, 11, 12, 13, 14, 15, 16, 17, 18, 19, 20, 21, 22, 23, 32, 33, 34, 35, 36, 48, 49, 50, 51, 64, 65, 66, 80, 81, 96, 97, 112, 113, 128, 144, 160, 176, 192, 208, 224, 240, 255, 255, 255, 255, 255, 255, 255, 255, 255, 255, 255, 255, 255, 255};
;           const int code = PAIRS[ch * 16 + i];
;           if (code == 255) { wk[i] = -3.0e38f; }
;           else { const float sm = s1[code >> 4] + s2[code & 15]; wk[i] = __uint_as_float((__float_as_uint(sm) & ~255u) | (unsigned)code); }
;         }
;         if (ch == 0) {
; #pragma unroll
;           for (int i = 0; i < 16; ++i) v[i] = wk[i];
;         } else {
;           bitonic_sort16(wk);
;           merge_top16(v, wk);
;         }
	v_add_f32_e32 v153, v141, v153
	v_add_f32_e32 v154, v141, v154
	v_add_f32_e32 v141, v141, v155
	v_and_b32_e32 v143, 0xffffff80, v143
	v_and_or_b32 v178, v178, s87, 20
	v_and_or_b32 v153, v153, s87, 21
	v_and_or_b32 v154, v154, s87, 22
	v_and_or_b32 v141, v141, s87, 23
	v_add_f32_e32 v155, v142, v140
	v_add_f32_e32 v179, v142, v156
	v_max_f32_e32 v184, v166, v174
	v_min_f32_e32 v166, v166, v174
	v_max_f32_e32 v174, v175, v175
	v_max_f32_e32 v175, v176, v176
	v_and_or_b32 v155, v155, s87, 32
	v_and_or_b32 v179, v179, s87, 33
	v_add_f32_e32 v180, v142, v157
	v_add_f32_e32 v181, v142, v158
	v_add_f32_e32 v142, v142, v152
	v_add_f32_e32 v152, v143, v140
	v_max_f32_e32 v176, v175, v174
	v_min_f32_e32 v174, v175, v174
	v_max_f32_e32 v175, v178, v178
	v_and_or_b32 v180, v180, s87, 34
	v_and_or_b32 v181, v181, s87, 35
	v_and_or_b32 v142, v142, s87, 36
	v_and_or_b32 v152, v152, s87, 48
	v_add_f32_e32 v182, v143, v156
	v_add_f32_e32 v183, v143, v157
	v_max_f32_e32 v178, v175, v153
	v_min_f32_e32 v153, v175, v153
	v_max_f32_e32 v175, v141, v154
	v_min_f32_e32 v141, v141, v154
	v_max_f32_e32 v154, v179, v179
	v_and_or_b32 v182, v182, s87, 49
	v_and_or_b32 v183, v183, s87, 50
	v_max_f32_e32 v179, v155, v154
	v_min_f32_e32 v154, v155, v154
	v_max_f32_e32 v155, v180, v180
	v_max_f32_e32 v180, v181, v181
	v_max_f32_e32 v181, v180, v155
	v_min_f32_e32 v155, v180, v155
	v_max_f32_e32 v180, v142, v152
	v_min_f32_e32 v142, v142, v152
	v_max_f32_e32 v152, v182, v182
	v_max_f32_e32 v182, v183, v183
	v_max_f32_e32 v183, v182, v152
	v_min_f32_e32 v152, v182, v152
	v_max_f32_e32 v182, v184, v174
	v_min_f32_e32 v174, v184, v174
	v_max_f32_e32 v184, v166, v176
	v_min_f32_e32 v166, v166, v176
	v_max_f32_e32 v176, v141, v178
	v_min_f32_e32 v141, v141, v178
	v_max_f32_e32 v178, v175, v153
	v_min_f32_e32 v153, v175, v153
	v_max_f32_e32 v175, v179, v155
	v_min_f32_e32 v155, v179, v155
	v_max_f32_e32 v179, v154, v181
	v_min_f32_e32 v154, v154, v181
	v_max_f32_e32 v181, v152, v180
	v_min_f32_e32 v152, v152, v180
	v_max_f32_e32 v180, v183, v142
	v_min_f32_e32 v142, v183, v142
	v_max_f32_e32 v183, v182, v184
	v_min_f32_e32 v182, v182, v184
	v_max_f32_e32 v184, v174, v166
	v_min_f32_e32 v166, v174, v166
	v_max_f32_e32 v174, v153, v141
	v_min_f32_e32 v141, v153, v141
	v_max_f32_e32 v153, v178, v176
	v_min_f32_e32 v176, v178, v176
	v_max_f32_e32 v178, v175, v179
	v_min_f32_e32 v175, v175, v179
	v_max_f32_e32 v179, v155, v154
	v_min_f32_e32 v154, v155, v154
	v_max_f32_e32 v155, v142, v152
	v_min_f32_e32 v142, v142, v152
	v_max_f32_e32 v152, v180, v181
	v_min_f32_e32 v180, v180, v181
	v_max_f32_e32 v181, v183, v141
	v_min_f32_e32 v141, v183, v141
	v_max_f32_e32 v183, v182, v174
	v_min_f32_e32 v174, v182, v174
	v_max_f32_e32 v182, v184, v176
	v_min_f32_e32 v176, v184, v176
	v_max_f32_e32 v184, v166, v153
	v_min_f32_e32 v153, v166, v153
	v_max_f32_e32 v166, v142, v178
	v_min_f32_e32 v142, v142, v178
	v_max_f32_e32 v178, v155, v175
	v_min_f32_e32 v155, v155, v175
	v_max_f32_e32 v175, v180, v179
	v_min_f32_e32 v179, v180, v179
	v_max_f32_e32 v180, v152, v154
	v_min_f32_e32 v152, v152, v154
	v_max_f32_e32 v154, v181, v182
	v_min_f32_e32 v181, v181, v182
	v_max_f32_e32 v182, v183, v184
	v_min_f32_e32 v183, v183, v184
	v_max_f32_e32 v184, v141, v176
	v_min_f32_e32 v141, v141, v176
	v_max_f32_e32 v176, v174, v153
	v_min_f32_e32 v153, v174, v153
	v_max_f32_e32 v174, v179, v142
	v_min_f32_e32 v142, v179, v142
	v_max_f32_e32 v179, v152, v155
	v_min_f32_e32 v152, v152, v155
	v_max_f32_e32 v155, v175, v166
	v_min_f32_e32 v166, v175, v166
	v_max_f32_e32 v175, v180, v178
	v_min_f32_e32 v178, v180, v178
	v_max_f32_e32 v180, v154, v182
	v_min_f32_e32 v154, v154, v182
	v_max_f32_e32 v182, v181, v183
	v_min_f32_e32 v181, v181, v183
	v_max_f32_e32 v183, v184, v176
	v_min_f32_e32 v176, v184, v176
	v_max_f32_e32 v184, v141, v153
	v_min_f32_e32 v141, v141, v153
	v_max_f32_e32 v153, v152, v142
	v_min_f32_e32 v142, v152, v142
	v_max_f32_e32 v152, v179, v174
	v_min_f32_e32 v174, v179, v174
	v_max_f32_e32 v179, v178, v166
	v_min_f32_e32 v166, v178, v166
	v_max_f32_e32 v178, v175, v155
	v_min_f32_e32 v155, v175, v155
	v_max_f32_e32 v175, v180, v142
	v_min_f32_e32 v142, v180, v142
	v_max_f32_e32 v180, v154, v153
	v_min_f32_e32 v153, v154, v153
	v_max_f32_e32 v154, v182, v174
	v_min_f32_e32 v174, v182, v174
	v_max_f32_e32 v182, v181, v152
	v_min_f32_e32 v152, v181, v152
	v_max_f32_e32 v181, v183, v166
	v_min_f32_e32 v166, v183, v166
	v_max_f32_e32 v183, v176, v179
	v_min_f32_e32 v176, v176, v179
	v_max_f32_e32 v179, v184, v155
	v_min_f32_e32 v155, v184, v155
	v_max_f32_e32 v184, v141, v178
	v_min_f32_e32 v141, v141, v178
	v_max_f32_e32 v178, v175, v181
	v_min_f32_e32 v175, v175, v181
	v_max_f32_e32 v181, v180, v183
	v_min_f32_e32 v180, v180, v183
	v_max_f32_e32 v183, v154, v179
	v_min_f32_e32 v154, v154, v179
	v_max_f32_e32 v179, v182, v184
	v_min_f32_e32 v182, v182, v184
	v_and_b32_e32 v136, 0xffffff80, v136
	v_and_b32_e32 v137, 0xffffff80, v137
	v_and_or_b32 v151, v151, s87, 11
	v_max_f32_e32 v184, v142, v166
	v_min_f32_e32 v142, v142, v166
	v_max_f32_e32 v166, v153, v176
	v_min_f32_e32 v153, v153, v176
	v_max_f32_e32 v176, v174, v155
	v_min_f32_e32 v155, v174, v155
	v_max_f32_e32 v174, v152, v141
	v_min_f32_e32 v141, v152, v141
	v_max_f32_e32 v152, v178, v183
	v_min_f32_e32 v178, v178, v183
	v_max_f32_e32 v183, v181, v179
	v_min_f32_e32 v179, v181, v179
	v_max_f32_e32 v181, v175, v154
	v_min_f32_e32 v154, v175, v154
	v_max_f32_e32 v175, v180, v182
	v_and_b32_e32 v138, 0xffffff80, v138
	v_and_or_b32 v171, v171, s87, 5
	v_min_f32_e32 v180, v180, v182
	v_max_f32_e32 v182, v184, v176
	v_min_f32_e32 v176, v184, v176
; DI void ce_desc(float& hi, float& lo) { const float a = hi, b = lo; hi = fmaxf(a, b); lo = fminf(a, b); }
; DI void bitonic_sort16(float (&v)[16]) {
; #pragma unroll
;   for (int k = 2; k <= 16; k <<= 1)
; #pragma unroll
;     for (int j = k >> 1; j > 0; j >>= 1)
; #pragma unroll
;       for (int i = 0; i < 16; ++i) {
;         const int l = i ^ j;
;         if (l > i) { if ((i & k) == 0 || k == 16) ce_desc(v[i], v[l]); else ce_desc(v[l], v[i]); }
;       }
; }
; DI void merge_top16(float (&v)[16], const float (&w)[16]) {
; #pragma unroll
;   for (int i = 0; i < 16; ++i) v[i] = fmaxf(v[i], w[15 - i]);
;   bitonic_merge16(v);
; DI void gemm256_tile(const Params& p, int mode, int layer, const u16* R, const u16* Cc, int brow, int bcol, lchar* shm, int tid_in, int wid) {
;     ...
; #pragma unroll
;       for (int ch = 0; ch < 4; ++ch) {
;         float wk[16];
; #pragma unroll
;         for (int i = 0; i < 16; ++i) {
;           constexpr unsigned char PAIRS[64] = {0, 1, 2, 3, 4, 5, 6, 7, 8, 9, 10, 11, 12, 13, 14, 15, 16, 17, 18, 19, 20, 21, 22, 23, 32, 33, 34, 35, 36, 48, 49, 50, 51, 64, 65, 66, 80, 81, 96, 97, 112, 113, 128, 144, 160, 176, 192, 208, 224, 240, 255, 255, 255, 255, 255, 255, 255, 255, 255, 255, 255, 255, 255, 255};
;           const int code = PAIRS[ch * 16 + i];
;           if (code == 255) { wk[i] = -3.0e38f; }
;           else { const float sm = s1[code >> 4] + s2[code & 15]; wk[i] = __uint_as_float((__float_as_uint(sm) & ~255u) | (unsigned)code); }
;         }
;         if (ch == 0) {
; #pragma unroll
;           for (int i = 0; i < 16; ++i) v[i] = wk[i];
;         } else {
;           bitonic_sort16(wk);
;           merge_top16(v, wk);
;         }
	v_max_f32_e32 v184, v166, v174
	v_min_f32_e32 v166, v166, v174
	v_min_f32_e32 v186, v181, v175
	v_max3_f32 v151, v151, v181, v175
	v_add_f32_e32 v143, v143, v158
	v_add_f32_e32 v158, v136, v140
	v_add_f32_e32 v175, v136, v156
	v_add_f32_e32 v136, v136, v157
	v_add_f32_e32 v157, v137, v140
	v_add_f32_e32 v137, v137, v156
	v_and_b32_e32 v139, 0xffffff80, v139
	v_and_b32_e32 v132, 0xffffff80, v132
	v_and_b32_e32 v133, 0xffffff80, v133
	v_and_or_b32 v145, v145, s87, 13
	v_min_f32_e32 v189, v176, v166
	v_max3_f32 v166, v171, v176, v166
	v_and_or_b32 v143, v143, s87, 51
	v_and_or_b32 v158, v158, s87, 64
	v_and_b32_e32 v175, 0xffffff00, v175
	v_and_b32_e32 v136, 0xffffff00, v136
	v_and_b32_e32 v157, 0xffffff00, v157
	v_and_b32_e32 v137, 0xffffff00, v137
	v_add_f32_e32 v176, v138, v140
	v_add_f32_e32 v138, v138, v156
	v_and_b32_e32 v134, 0xffffff80, v134
	v_and_b32_e32 v135, 0xffffff80, v135
	v_min_f32_e32 v185, v178, v179
	v_max3_f32 v145, v145, v178, v179
	v_or_b32_e32 v175, 0x41, v175
	v_or_b32_e32 v136, 0x42, v136
	v_or_b32_e32 v157, 0x50, v157
	v_or_b32_e32 v137, 0x51, v137
	v_and_b32_e32 v176, 0xffffff00, v176
	v_and_b32_e32 v138, 0xffffff00, v138
	v_add_f32_e32 v178, v139, v140
	v_add_f32_e32 v139, v139, v156
	v_add_f32_e32 v132, v132, v140
	v_add_f32_e32 v133, v133, v140
	v_or_b32_e32 v176, 0x60, v176
	v_or_b32_e32 v138, 0x61, v138
	v_and_b32_e32 v178, 0xffffff00, v178
	v_and_b32_e32 v139, 0xffffff00, v139
	v_and_b32_e32 v132, 0xffffff00, v132
	v_and_b32_e32 v133, 0xffffff00, v133
	v_add_f32_e32 v134, v134, v140
	v_add_f32_e32 v135, v135, v140
	v_add_f32_e32 v156, v159, v140
	v_add_f32_e32 v159, v167, v140
	v_max_f32_e32 v167, v143, v158
	v_min_f32_e32 v143, v143, v158
	v_max_f32_e32 v158, v175, v175
	v_or_b32_e32 v178, 0x70, v178
	v_or_b32_e32 v139, 0x71, v139
	v_or_b32_e32 v132, 0x80, v132
	v_or_b32_e32 v133, 0x90, v133
	v_and_b32_e32 v134, 0xffffff00, v134
	v_and_b32_e32 v135, 0xffffff00, v135
	v_max_f32_e32 v175, v136, v158
	v_min_f32_e32 v136, v136, v158
	v_max_f32_e32 v158, v157, v137
	v_min_f32_e32 v137, v157, v137
	v_max_f32_e32 v157, v176, v176
	v_or_b32_e32 v134, 0xa0, v134
	v_or_b32_e32 v135, 0xb0, v135
	v_and_b32_e32 v156, 0xffffff00, v156
	v_and_b32_e32 v159, 0xffffff00, v159
	v_max_f32_e32 v176, v138, v157
	v_min_f32_e32 v138, v138, v157
	v_max_f32_e32 v157, v178, v178
	v_or_b32_e32 v156, 0xc0, v156
	v_or_b32_e32 v159, 0xd0, v159
	v_max_f32_e32 v178, v157, v139
	v_min_f32_e32 v139, v157, v139
	v_max_f32_e32 v157, v133, v132
	v_min_f32_e32 v132, v133, v132
	v_max_f32_e32 v133, v135, v135
	v_max_f32_e32 v135, v134, v133
	v_min_f32_e32 v133, v134, v133
	v_max_f32_e32 v134, v156, v156
	v_max_f32_e32 v156, v159, v159
	v_max_f32_e32 v159, v156, v134
	v_min_f32_e32 v134, v156, v134
	v_max_f32_e32 v156, v167, v136
	v_min_f32_e32 v136, v167, v136
	v_max_f32_e32 v167, v143, v175
	v_min_f32_e32 v143, v143, v175
	v_max_f32_e32 v175, v138, v158
	v_min_f32_e32 v138, v138, v158
	v_max_f32_e32 v158, v176, v137
	v_min_f32_e32 v137, v176, v137
	v_max_f32_e32 v176, v178, v132
	v_min_f32_e32 v132, v178, v132
	v_max_f32_e32 v178, v139, v157
	v_min_f32_e32 v139, v139, v157
	v_max_f32_e32 v157, v134, v135
	v_min_f32_e32 v134, v134, v135
	v_max_f32_e32 v135, v159, v133
	v_min_f32_e32 v133, v159, v133
	v_max_f32_e32 v159, v156, v167
	v_min_f32_e32 v156, v156, v167
	v_max_f32_e32 v167, v136, v143
	v_min_f32_e32 v136, v136, v143
	v_max_f32_e32 v143, v137, v138
	v_min_f32_e32 v137, v137, v138
	v_max_f32_e32 v138, v158, v175
	v_min_f32_e32 v158, v158, v175
	v_max_f32_e32 v175, v176, v178
	v_min_f32_e32 v176, v176, v178
	v_max_f32_e32 v178, v132, v139
	v_min_f32_e32 v132, v132, v139
	v_max_f32_e32 v139, v133, v134
	v_min_f32_e32 v133, v133, v134
	v_max_f32_e32 v134, v135, v157
	v_min_f32_e32 v135, v135, v157
	v_and_b32_e32 v146, 0xffffff00, v146
	v_and_or_b32 v147, v147, s87, 1
	v_and_or_b32 v168, v168, s87, 2
	v_and_or_b32 v169, v169, s87, 3
	v_and_or_b32 v170, v170, s87, 4
	v_and_or_b32 v172, v172, s87, 6
	v_and_or_b32 v148, v148, s87, 8
	v_and_or_b32 v150, v150, s87, 10
	v_and_or_b32 v144, v144, s87, 12
	v_and_or_b32 v130, v130, s87, 14
	v_max_f32_e32 v174, v142, v155
	v_min_f32_e32 v142, v142, v155
	v_max_f32_e32 v155, v153, v141
	v_min_f32_e32 v141, v153, v141
	v_max_f32_e32 v157, v159, v137
	v_min_f32_e32 v137, v159, v137
	v_max_f32_e32 v159, v156, v143
	v_min_f32_e32 v143, v156, v143
	v_max_f32_e32 v156, v167, v158
	v_min_f32_e32 v158, v167, v158
	v_max_f32_e32 v167, v136, v138
	v_min_f32_e32 v136, v136, v138
	v_max_f32_e32 v138, v133, v175
	v_min_f32_e32 v133, v133, v175
	v_max_f32_e32 v175, v139, v176
	v_min_f32_e32 v139, v139, v176
	v_max_f32_e32 v176, v135, v178
	v_min_f32_e32 v135, v135, v178
	v_max_f32_e32 v178, v134, v132
	v_min_f32_e32 v132, v134, v132
	v_and_or_b32 v173, v173, s87, 7
	v_and_or_b32 v149, v149, s87, 9
	v_and_or_b32 v131, v131, s87, 15
	v_min_f32_e32 v153, v152, v183
	v_min_f32_e32 v187, v154, v180
	v_min_f32_e32 v188, v182, v184
	v_min_f32_e32 v190, v174, v155
	v_min_f32_e32 v191, v142, v141
	v_max3_f32 v141, v147, v142, v141
	v_max3_f32 v147, v169, v174, v155
	v_max_f32_e32 v134, v157, v156
	v_min_f32_e32 v156, v157, v156
	v_max_f32_e32 v157, v159, v167
	v_min_f32_e32 v159, v159, v167
	v_max_f32_e32 v167, v137, v158
	v_min_f32_e32 v137, v137, v158
	v_max_f32_e32 v158, v143, v136
	v_min_f32_e32 v136, v143, v136
	v_max_f32_e32 v143, v135, v133
	v_min_f32_e32 v133, v135, v133
	v_max_f32_e32 v135, v132, v139
	v_min_f32_e32 v132, v132, v139
	v_max_f32_e32 v139, v176, v138
	v_min_f32_e32 v138, v176, v138
	v_max_f32_e32 v176, v178, v175
	v_min_f32_e32 v175, v178, v175
	v_max_f32_e32 v146, v146, v191
	v_max_f32_e32 v142, v168, v190
; DI void merge_top16(float (&v)[16], const float (&w)[16]) {
; #pragma unroll
;   for (int i = 0; i < 16; ++i) v[i] = fmaxf(v[i], w[15 - i]);
;   bitonic_merge16(v);
; DI void gemm256_tile(const Params& p, int mode, int layer, const u16* R, const u16* Cc, int brow, int bcol, lchar* shm, int tid_in, int wid) {
;     ...
; #pragma unroll
;       for (int ch = 0; ch < 4; ++ch) {
;         float wk[16];
; #pragma unroll
;         for (int i = 0; i < 16; ++i) {
;           constexpr unsigned char PAIRS[64] = {0, 1, 2, 3, 4, 5, 6, 7, 8, 9, 10, 11, 12, 13, 14, 15, 16, 17, 18, 19, 20, 21, 22, 23, 32, 33, 34, 35, 36, 48, 49, 50, 51, 64, 65, 66, 80, 81, 96, 97, 112, 113, 128, 144, 160, 176, 192, 208, 224, 240, 255, 255, 255, 255, 255, 255, 255, 255, 255, 255, 255, 255, 255, 255};
;           const int code = PAIRS[ch * 16 + i];
;           if (code == 255) { wk[i] = -3.0e38f; }
;           else { const float sm = s1[code >> 4] + s2[code & 15]; wk[i] = __uint_as_float((__float_as_uint(sm) & ~255u) | (unsigned)code); }
;         }
;         if (ch == 0) {
; #pragma unroll
;           for (int i = 0; i < 16; ++i) v[i] = wk[i];
;         } else {
;           bitonic_sort16(wk);
;           merge_top16(v, wk);
;         }
	v_max_f32_e32 v155, v170, v189
	v_max_f32_e32 v168, v172, v188
	v_max3_f32 v169, v173, v182, v184
	v_max_f32_e32 v148, v148, v187
	v_max3_f32 v149, v149, v154, v180
	v_max_f32_e32 v150, v150, v186
	v_max_f32_e32 v144, v144, v185
	v_max_f32_e32 v130, v130, v153
	v_max3_f32 v131, v131, v152, v183
	v_max_f32_e32 v178, v134, v157
	v_min_f32_e32 v134, v134, v157
	v_max_f32_e32 v157, v156, v159
	v_min_f32_e32 v156, v156, v159
	v_max_f32_e32 v159, v167, v158
	v_min_f32_e32 v158, v167, v158
	v_max_f32_e32 v167, v137, v136
	v_min_f32_e32 v136, v137, v136
	v_max_f32_e32 v137, v132, v133
	v_min_f32_e32 v132, v132, v133
	v_max_f32_e32 v133, v135, v143
	v_min_f32_e32 v135, v135, v143
	v_max_f32_e32 v143, v175, v138
	v_min_f32_e32 v138, v175, v138
	v_max_f32_e32 v175, v176, v139
	v_min_f32_e32 v139, v176, v139
	v_add_f32_e32 v129, v129, v140
	v_add_f32_e32 v128, v128, v140
	v_max_f32_e32 v152, v146, v148
	v_min_f32_e32 v146, v146, v148
	v_max_f32_e32 v148, v141, v149
	v_min_f32_e32 v141, v141, v149
	v_max_f32_e32 v149, v142, v150
	v_min_f32_e32 v142, v142, v150
	v_max_f32_e32 v150, v147, v151
	v_min_f32_e32 v147, v147, v151
	v_max_f32_e32 v151, v155, v144
	v_min_f32_e32 v144, v155, v144
	v_max_f32_e32 v153, v166, v145
	v_max_f32_e32 v154, v168, v130
	v_max_f32_e32 v155, v169, v131
	v_max_f32_e32 v176, v178, v132
	v_min_f32_e32 v132, v178, v132
	v_max_f32_e32 v178, v134, v137
	v_min_f32_e32 v134, v134, v137
	v_max_f32_e32 v137, v157, v135
	v_min_f32_e32 v135, v157, v135
	v_max_f32_e32 v157, v156, v133
	v_min_f32_e32 v133, v156, v133
	v_max_f32_e32 v156, v159, v138
	v_min_f32_e32 v138, v159, v138
	v_max_f32_e32 v159, v158, v143
	v_min_f32_e32 v143, v158, v143
	v_max_f32_e32 v158, v167, v139
	v_min_f32_e32 v139, v167, v139
	v_max_f32_e32 v167, v136, v175
	v_min_f32_e32 v136, v136, v175
	v_and_b32_e32 v129, 0xffffff00, v129
	v_and_b32_e32 v128, 0xffffff00, v128
	v_min_f32_e32 v145, v166, v145
	v_min_f32_e32 v130, v168, v130
	v_min_f32_e32 v131, v169, v131
	v_max_f32_e32 v166, v152, v151
	v_min_f32_e32 v151, v152, v151
	v_max_f32_e32 v152, v148, v153
	v_min_f32_e32 v148, v148, v153
	v_max_f32_e32 v153, v149, v154
	v_min_f32_e32 v149, v149, v154
	v_max_f32_e32 v154, v150, v155
	v_max_f32_e32 v175, v176, v156
	v_min_f32_e32 v156, v176, v156
	v_max_f32_e32 v176, v178, v159
	v_min_f32_e32 v159, v178, v159
	v_max_f32_e32 v178, v137, v158
	v_min_f32_e32 v137, v137, v158
	v_max_f32_e32 v158, v157, v167
	v_min_f32_e32 v157, v157, v167
	v_max_f32_e32 v167, v132, v138
	v_min_f32_e32 v132, v132, v138
	v_max_f32_e32 v138, v134, v143
	v_min_f32_e32 v134, v134, v143
	v_max_f32_e32 v143, v135, v139
	v_min_f32_e32 v135, v135, v139
	v_max_f32_e32 v139, v133, v136
	v_or_b32_e32 v129, 0xe0, v129
	v_or_b32_e32 v128, 0xf0, v128
	v_min_f32_e32 v150, v150, v155
	v_max_f32_e32 v155, v146, v144
	v_min_f32_e32 v144, v146, v144
	v_max_f32_e32 v146, v141, v145
	v_min_f32_e32 v141, v141, v145
	v_max_f32_e32 v145, v142, v130
	v_min_f32_e32 v130, v142, v130
	v_max_f32_e32 v142, v147, v131
	v_min_f32_e32 v131, v147, v131
	v_max_f32_e32 v147, v166, v153
	v_min_f32_e32 v153, v166, v153
	v_max_f32_e32 v166, v152, v154
	v_min_f32_e32 v133, v133, v136
	v_max_f32_e32 v136, v175, v178
	v_min_f32_e32 v175, v175, v178
	v_max_f32_e32 v178, v176, v158
	v_min_f32_e32 v158, v176, v158
	v_max_f32_e32 v176, v156, v137
	v_min_f32_e32 v137, v156, v137
	v_max_f32_e32 v156, v159, v157
	v_min_f32_e32 v157, v159, v157
	v_max_f32_e32 v159, v167, v143
	v_min_f32_e32 v143, v167, v143
	v_max_f32_e32 v167, v138, v139
	v_min_f32_e32 v152, v152, v154
	v_max_f32_e32 v154, v151, v149
	v_min_f32_e32 v149, v151, v149
	v_max_f32_e32 v151, v148, v150
	v_min_f32_e32 v148, v148, v150
	v_max_f32_e32 v150, v155, v145
	v_min_f32_e32 v145, v155, v145
	v_max_f32_e32 v155, v146, v142
	v_min_f32_e32 v142, v146, v142
	v_max_f32_e32 v146, v144, v130
	v_min_f32_e32 v130, v144, v130
	v_max_f32_e32 v144, v141, v131
	v_min_f32_e32 v131, v141, v131
	v_min_f32_e32 v141, v147, v166
	v_min_f32_e32 v138, v138, v139
	v_max_f32_e32 v139, v132, v135
	v_min_f32_e32 v132, v132, v135
	v_max_f32_e32 v135, v134, v133
	v_min_f32_e32 v133, v134, v133
	v_min_f32_e32 v181, v137, v157
	v_min_f32_e32 v182, v159, v167
	v_max_f32_e32 v140, v129, v128
	v_min_f32_e32 v128, v129, v128
	v_min_f32_e32 v170, v149, v148
	v_min_f32_e32 v171, v150, v155
	v_min_f32_e32 v172, v145, v142
	v_min_f32_e32 v173, v146, v144
	v_min_f32_e32 v179, v175, v158
	v_min_f32_e32 v180, v176, v156
	v_min_f32_e32 v185, v132, v133
	v_max3_f32 v132, v141, v132, v133
	v_max3_f32 v141, v149, v148, v182
	v_max3_f32 v148, v150, v155, v181
	v_max_f32_e32 v155, 0xff61b1e6, v140
	v_max_f32_e32 v129, 0xff61b1e6, v128
	v_min_f32_e32 v140, 0xff61b1e6, v140
	v_min_f32_e32 v128, 0xff61b1e6, v128
	v_min_f32_e32 v169, v154, v151
	v_max3_f32 v142, v145, v142, v180
	v_max3_f32 v145, v172, v176, v156
	v_max3_f32 v144, v146, v144, v179
	v_max3_f32 v146, v173, v175, v158
	v_max_f32_e32 v156, v155, v129
	v_max_f32_e32 v158, v140, v128
	v_min_f32_e32 v129, v155, v129
	v_min_f32_e32 v128, v140, v128
	v_min_f32_e32 v183, v143, v138
	v_max3_f32 v138, v169, v143, v138
	v_max3_f32 v143, v170, v159, v167
	v_max3_f32 v137, v171, v137, v157
	v_max_f32_e32 v157, 0xff61b1e6, v156
	v_max_f32_e32 v159, 0xff61b1e6, v158
	v_max_f32_e32 v155, 0xff61b1e6, v129
	v_max_f32_e32 v140, 0xff61b1e6, v128
	v_min_f32_e32 v156, 0xff61b1e6, v156
	v_min_f32_e32 v158, 0xff61b1e6, v158
	v_min_f32_e32 v129, 0xff61b1e6, v129
	v_min_f32_e32 v128, 0xff61b1e6, v128
	v_min_f32_e32 v168, v153, v152
	v_max3_f32 v147, v147, v166, v185
	v_max_f32_e32 v166, v157, v159
	v_max_f32_e32 v167, v155, v140
	v_max_f32_e32 v170, v156, v158
; DI void ce_desc(float& hi, float& lo) { const float a = hi, b = lo; hi = fmaxf(a, b); lo = fminf(a, b); }
; DI void bitonic_merge16(float (&v)[16]) {
; #pragma unroll
;   for (int j = 8; j > 0; j >>= 1)
; #pragma unroll
;     for (int i = 0; i < 16; ++i) if ((i & j) == 0) ce_desc(v[i], v[i | j]);
; }
; DI void bitonic_sort16(float (&v)[16]) {
; #pragma unroll
;   for (int k = 2; k <= 16; k <<= 1)
; #pragma unroll
;     for (int j = k >> 1; j > 0; j >>= 1)
; #pragma unroll
;       for (int i = 0; i < 16; ++i) {
;         const int l = i ^ j;
;         if (l > i) { if ((i & k) == 0 || k == 16) ce_desc(v[i], v[l]); else ce_desc(v[l], v[i]); }
;       }
; }
; DI void merge_top16(float (&v)[16], const float (&w)[16]) {
; #pragma unroll
;   for (int i = 0; i < 16; ++i) v[i] = fmaxf(v[i], w[15 - i]);
;   bitonic_merge16(v);
; DI void gemm256_tile(const Params& p, int mode, int layer, const u16* R, const u16* Cc, int brow, int bcol, lchar* shm, int tid_in, int wid) {
;     ...
;       for (int ch = 0; ch < 4; ++ch) {
;         float wk[16];
; #pragma unroll
;         for (int i = 0; i < 16; ++i) {
;           constexpr unsigned char PAIRS[64] = {0, 1, 2, 3, 4, 5, 6, 7, 8, 9, 10, 11, 12, 13, 14, 15, 16, 17, 18, 19, 20, 21, 22, 23, 32, 33, 34, 35, 36, 48, 49, 50, 51, 64, 65, 66, 80, 81, 96, 97, 112, 113, 128, 144, 160, 176, 192, 208, 224, 240, 255, 255, 255, 255, 255, 255, 255, 255, 255, 255, 255, 255, 255, 255};
;           const int code = PAIRS[ch * 16 + i];
;           if (code == 255) { wk[i] = -3.0e38f; }
;           else { const float sm = s1[code >> 4] + s2[code & 15]; wk[i] = __uint_as_float((__float_as_uint(sm) & ~255u) | (unsigned)code); }
;         }
;         if (ch == 0) {
; #pragma unroll
;           for (int i = 0; i < 16; ++i) v[i] = wk[i];
;         } else {
;           bitonic_sort16(wk);
;           merge_top16(v, wk);
;         }
;       }
	v_max_f32_e32 v171, v129, v128
	v_min_f32_e32 v157, v157, v159
	v_min_f32_e32 v140, v155, v140
	v_min_f32_e32 v156, v156, v158
	v_min_f32_e32 v128, v129, v128
	v_min_f32_e32 v174, v130, v131
	v_min_f32_e32 v134, v136, v178
	v_min_f32_e32 v184, v139, v135
	v_max3_f32 v135, v168, v139, v135
	v_max_f32_e32 v168, v166, v167
	v_max_f32_e32 v172, v170, v171
	v_max_f32_e32 v155, v157, v140
	v_max_f32_e32 v129, v156, v128
	v_min_f32_e32 v166, v166, v167
	v_min_f32_e32 v170, v170, v171
	v_min_f32_e32 v140, v157, v140
	v_min_f32_e32 v128, v156, v128
	v_max3_f32 v133, v153, v152, v184
	v_max3_f32 v139, v154, v151, v183
	v_max3_f32 v130, v130, v131, v134
	v_max3_f32 v131, v174, v136, v178
	v_min_f32_e32 v169, 0xff61b1e6, v168
	v_min_f32_e32 v173, 0xff61b1e6, v172
	v_min_f32_e32 v159, 0xff61b1e6, v155
	v_min_f32_e32 v158, 0xff61b1e6, v129
	v_min_f32_e32 v167, 0xff61b1e6, v166
	v_min_f32_e32 v171, 0xff61b1e6, v170
	v_min_f32_e32 v157, 0xff61b1e6, v140
	v_min_f32_e32 v156, 0xff61b1e6, v128
	v_max_f32_e32 v134, v147, v148
	v_min_f32_e32 v136, v147, v148
	v_max_f32_e32 v147, v132, v137
	v_min_f32_e32 v132, v132, v137
	v_max_f32_e32 v137, v133, v142
	v_min_f32_e32 v133, v133, v142
	v_max_f32_e32 v142, v135, v145
	v_min_f32_e32 v135, v135, v145
	v_max_f32_e32 v145, v139, v144
	v_min_f32_e32 v139, v139, v144
	v_max_f32_e32 v144, v138, v146
	v_min_f32_e32 v138, v138, v146
	v_max_f32_e32 v146, v141, v130
	v_min_f32_e32 v130, v141, v130
	v_max_f32_e32 v141, v143, v131
	v_min_f32_e32 v174, v169, v173
	v_min_f32_e32 v175, v159, v158
	v_min_f32_e32 v178, v167, v171
	v_min_f32_e32 v179, v157, v156
	v_min_f32_e32 v131, v143, v131
	v_max_f32_e32 v143, v134, v145
	v_min_f32_e32 v134, v134, v145
	v_max_f32_e32 v145, v147, v144
	v_min_f32_e32 v144, v147, v144
	v_max_f32_e32 v147, v137, v146
	v_min_f32_e32 v137, v137, v146
	v_max_f32_e32 v146, v142, v141
	v_min_f32_e32 v176, v174, v175
	v_min_f32_e32 v180, v178, v179
	v_max_f32_e32 v169, v169, v173
	v_max_f32_e32 v158, v159, v158
	v_max_f32_e32 v167, v167, v171
	v_max_f32_e32 v156, v157, v156
	v_min_f32_e32 v141, v142, v141
	v_max_f32_e32 v142, v136, v139
	v_min_f32_e32 v136, v136, v139
	v_max_f32_e32 v139, v132, v138
	v_min_f32_e32 v132, v132, v138
	v_max_f32_e32 v138, v133, v130
	v_min_f32_e32 v130, v133, v130
	v_max_f32_e32 v133, v135, v131
	v_min_f32_e32 v131, v135, v131
	v_max_f32_e32 v135, v143, v147
	v_min_f32_e32 v143, v143, v147
	v_max_f32_e32 v147, v145, v146
	v_min_f32_e32 v181, v176, v180
	v_min_f32_e32 v159, v169, v158
	v_min_f32_e32 v157, v167, v156
	v_min_f32_e32 v145, v145, v146
	v_max_f32_e32 v146, v134, v137
	v_min_f32_e32 v134, v134, v137
	v_max_f32_e32 v137, v144, v141
	v_min_f32_e32 v141, v144, v141
	v_max_f32_e32 v144, v142, v138
	v_min_f32_e32 v138, v142, v138
	v_max_f32_e32 v142, v139, v133
	v_min_f32_e32 v133, v139, v133
	v_max_f32_e32 v139, v136, v130
	v_min_f32_e32 v130, v136, v130
	v_max_f32_e32 v136, v132, v131
	v_min_f32_e32 v131, v132, v131
	v_min_f32_e32 v132, v135, v147
	v_max3_f32 v135, v135, v147, v181
	v_max_f32_e32 v147, 0xff61b1e6, v168
	v_max_f32_e32 v168, 0xff61b1e6, v172
	v_max_f32_e32 v155, 0xff61b1e6, v155
	v_max_f32_e32 v129, 0xff61b1e6, v129
	v_max_f32_e32 v166, 0xff61b1e6, v166
	v_max_f32_e32 v170, 0xff61b1e6, v170
	v_min_f32_e32 v171, v159, v157
	v_min_f32_e32 v149, v146, v137
	v_min_f32_e32 v172, v147, v168
	v_min_f32_e32 v181, v155, v129
	v_min_f32_e32 v183, v166, v170
	v_max_f32_e32 v140, 0xff61b1e6, v140
	v_max_f32_e32 v128, 0xff61b1e6, v128
	v_max3_f32 v137, v146, v137, v171
	v_max_f32_e32 v146, v147, v168
	v_max_f32_e32 v129, v155, v129
	v_max_f32_e32 v155, v166, v170
	v_max_f32_e32 v168, v174, v175
	v_max_f32_e32 v170, v178, v179
	v_min_f32_e32 v184, v140, v128
	v_max_f32_e32 v128, v140, v128
	v_min_f32_e32 v171, v168, v170
	v_max_f32_e32 v158, v169, v158
	v_max_f32_e32 v156, v167, v156
	v_min_f32_e32 v148, v143, v145
	v_min_f32_e32 v182, v172, v181
	v_min_f32_e32 v185, v183, v184
	v_min_f32_e32 v147, v146, v129
	v_min_f32_e32 v140, v155, v128
	v_max3_f32 v143, v143, v145, v171
	v_max_f32_e32 v145, v172, v181
	v_max_f32_e32 v171, v183, v184
	v_min_f32_e32 v167, v158, v156
	v_max_f32_e32 v129, v146, v129
	v_max_f32_e32 v128, v155, v128
	v_min_f32_e32 v150, v134, v141
	v_min_f32_e32 v151, v144, v142
	v_min_f32_e32 v152, v138, v133
	v_min_f32_e32 v153, v139, v136
	v_min_f32_e32 v154, v130, v131
	v_min_f32_e32 v186, v182, v185
	v_min_f32_e32 v166, v147, v140
	v_min_f32_e32 v172, v145, v171
	v_max3_f32 v134, v134, v141, v167
	v_min_f32_e32 v141, v129, v128
	v_max3_f32 v142, v144, v142, v186
	v_max3_f32 v136, v139, v136, v166
	v_max3_f32 v133, v138, v133, v172
	v_max3_f32 v130, v130, v131, v141
	v_max3_f32 v132, v132, v176, v180
	v_max3_f32 v151, v151, v182, v185
	v_max3_f32 v149, v149, v159, v157
	v_max3_f32 v140, v153, v147, v140
	v_max3_f32 v148, v148, v168, v170
	v_max3_f32 v145, v152, v145, v171
	v_max3_f32 v150, v150, v158, v156
	v_max3_f32 v128, v154, v129, v128
	v_min_f32_e32 v144, v135, v142
	v_min_f32_e32 v139, v137, v136
	v_min_f32_e32 v138, v143, v133
	v_min_f32_e32 v131, v134, v130
	v_min_f32_e32 v155, v132, v151
	v_min_f32_e32 v147, v149, v140
	v_min_f32_e32 v152, v148, v145
	v_min_f32_e32 v129, v150, v128
	v_min_f32_e32 v166, v144, v139
	v_min_f32_e32 v141, v138, v131
	v_min_f32_e32 v153, v155, v147
	v_min_f32_e32 v154, v152, v129
	v_min_f32_e32 v146, v166, v141
	v_min_f32_e32 v156, v153, v154
	v_min_f32_e32 v157, v146, v156
	v_max_f32_e32 v156, v146, v156
	v_max_f32_e32 v141, v166, v141
	v_max_f32_e32 v146, v153, v154
	v_min_f32_e32 v153, v141, v146
	v_max_f32_e32 v154, v141, v146
	v_max_f32_e32 v139, v144, v139
	v_max_f32_e32 v131, v138, v131
; DI float fast_exp2(float x) { return __builtin_amdgcn_exp2f(x); }
; DI void gemm256_tile(const Params& p, int mode, int layer, const u16* R, const u16* Cc, int brow, int bcol, lchar* shm, int tid_in, int wid) {
;     ...
;           merge_top16(v, wk);
;         }
;       }
;       float e[16], sum = 0.f;
;       const float mx = __uint_as_float(__float_as_uint(v[0]) & ~255u);
; #pragma unroll
;       for (int j = 0; j < 16; ++j) { e[j] = fast_exp2((__uint_as_float(__float_as_uint(v[j]) & ~255u) - mx) * LOG2E); sum += e[j]; }
;       const float inv = 1.0f / sum;
;       const int hd = brow >> 8;
;       u16* di = W_IDX(p) + (size_t)(bcol + tok) * 128 + hd * 16;
;       float* dg = W_G(p) + (size_t)(bcol + tok) * 128 + hd * 16;
;       unsigned eid[16];
; #pragma unroll
;       for (int k = 0; k < 16; ++k) {
;         const unsigned code = __float_as_uint(v[k]) & 255u;
;         const unsigned i1 = LL[tok * 32 + (((code >> 4) + tok) & 31)] & 127u, i2 = LL[tok * 32 + ((16 + (code & 15u) + tok) & 31)] & 127u;
;         eid[k] = i1 * 128u + i2;
	v_max_f32_e32 v141, v155, v147
	v_max_f32_e32 v129, v152, v129
	v_min_f32_e32 v138, v139, v131
	v_min_f32_e32 v144, v141, v129
	v_max_f32_e32 v131, v139, v131
	v_max_f32_e32 v129, v141, v129
	v_min_f32_e32 v158, v131, v129
	v_max_f32_e32 v159, v131, v129
	v_max_f32_e32 v129, v135, v142
	v_max_f32_e32 v131, v137, v136
	v_max_f32_e32 v133, v143, v133
	v_max_f32_e32 v130, v134, v130
	v_max_f32_e32 v132, v132, v151
	v_max_f32_e32 v137, v149, v140
	v_max_f32_e32 v139, v148, v145
	v_max_f32_e32 v128, v150, v128
	v_min_f32_e32 v152, v138, v144
	v_max_f32_e32 v155, v138, v144
	v_min_f32_e32 v135, v129, v131
	v_min_f32_e32 v134, v133, v130
	v_min_f32_e32 v138, v132, v137
	v_min_f32_e32 v140, v139, v128
	v_max_f32_e32 v129, v129, v131
	v_max_f32_e32 v130, v133, v130
	v_max_f32_e32 v132, v132, v137
	v_max_f32_e32 v128, v139, v128
	v_min_f32_e32 v131, v129, v130
	v_min_f32_e32 v133, v132, v128
	v_max_f32_e32 v129, v129, v130
	v_max_f32_e32 v128, v132, v128
	v_max_f32_e32 v169, v129, v128
	v_max_f32_e32 v167, v131, v133
	v_min_f32_e32 v168, v129, v128
	v_and_b32_e32 v145, 0xffffff00, v169
	v_and_b32_e32 v129, 0xffffff00, v168
	v_and_b32_e32 v130, 0xffffff00, v167
	v_sub_f32_e32 v128, v145, v145
	v_min_f32_e32 v166, v131, v133
	v_mul_f32_e32 v128, 0x3fb8aa3b, v128
	v_sub_f32_e32 v129, v129, v145
	v_sub_f32_e32 v130, v130, v145
	v_and_b32_e32 v131, 0xffffff00, v166
	v_exp_f32_e32 v128, v128
	v_mul_f32_e32 v129, 0x3fb8aa3b, v129
	v_mul_f32_e32 v130, 0x3fb8aa3b, v130
	v_exp_f32_e32 v129, v129
	v_exp_f32_e32 v132, v130
	v_sub_f32_e32 v130, v131, v145
	v_mul_f32_e32 v130, 0x3fb8aa3b, v130
	v_exp_f32_e32 v133, v130
	v_min_f32_e32 v136, v135, v134
	v_max_f32_e32 v134, v135, v134
	v_max_f32_e32 v135, v138, v140
	v_add_f32_e32 v130, 0, v128
	v_min_f32_e32 v141, v138, v140
	v_max_f32_e32 v151, v134, v135
	v_add_f32_e32 v130, v129, v130
	v_max_f32_e32 v149, v136, v141
	v_min_f32_e32 v150, v134, v135
	v_and_b32_e32 v134, 0xffffff00, v151
	v_add_f32_e32 v130, v132, v130
	v_min_f32_e32 v148, v136, v141
	v_and_b32_e32 v135, 0xffffff00, v150
	v_and_b32_e32 v136, 0xffffff00, v149
	v_add_f32_e32 v147, v133, v130
	v_sub_f32_e32 v130, v134, v145
	v_mul_f32_e32 v130, 0x3fb8aa3b, v130
	v_sub_f32_e32 v131, v135, v145
	v_sub_f32_e32 v134, v136, v145
	v_and_b32_e32 v137, 0xffffff00, v148
	v_exp_f32_e32 v130, v130
	v_mul_f32_e32 v131, 0x3fb8aa3b, v131
	v_mul_f32_e32 v134, 0x3fb8aa3b, v134
	v_exp_f32_e32 v131, v131
	v_exp_f32_e32 v136, v134
	v_sub_f32_e32 v134, v137, v145
	v_mul_f32_e32 v134, 0x3fb8aa3b, v134
	v_exp_f32_e32 v137, v134
	v_add_f32_e32 v134, v130, v147
	v_add_f32_e32 v134, v131, v134
	v_and_b32_e32 v138, 0xffffff00, v159
	v_add_f32_e32 v134, v136, v134
	v_and_b32_e32 v139, 0xffffff00, v158
	v_and_b32_e32 v140, 0xffffff00, v155
	v_add_f32_e32 v147, v137, v134
	v_sub_f32_e32 v134, v138, v145
	v_mul_f32_e32 v134, 0x3fb8aa3b, v134
	v_sub_f32_e32 v135, v139, v145
	v_sub_f32_e32 v138, v140, v145
	v_and_b32_e32 v141, 0xffffff00, v152
	v_exp_f32_e32 v134, v134
	v_mul_f32_e32 v135, 0x3fb8aa3b, v135
	v_mul_f32_e32 v138, 0x3fb8aa3b, v138
	v_exp_f32_e32 v135, v135
	v_exp_f32_e32 v140, v138
	v_sub_f32_e32 v138, v141, v145
	v_mul_f32_e32 v138, 0x3fb8aa3b, v138
	v_exp_f32_e32 v141, v138
	v_add_f32_e32 v138, v134, v147
	v_add_f32_e32 v138, v135, v138
	v_and_b32_e32 v142, 0xffffff00, v154
	v_add_f32_e32 v138, v140, v138
	v_and_b32_e32 v143, 0xffffff00, v153
	v_add_f32_e32 v147, v141, v138
	v_sub_f32_e32 v138, v142, v145
	v_and_b32_e32 v144, 0xffffff00, v156
	v_mul_f32_e32 v138, 0x3fb8aa3b, v138
	v_sub_f32_e32 v139, v143, v145
	v_and_b32_e32 v146, 0xffffff00, v157
	v_exp_f32_e32 v138, v138
	v_mul_f32_e32 v139, 0x3fb8aa3b, v139
	v_sub_f32_e32 v142, v144, v145
	v_exp_f32_e32 v139, v139
	v_mul_f32_e32 v142, 0x3fb8aa3b, v142
	v_sub_f32_e32 v143, v146, v145
	v_exp_f32_e32 v142, v142
	v_mul_f32_e32 v143, 0x3fb8aa3b, v143
	v_exp_f32_e32 v143, v143
	v_add_f32_e32 v144, v138, v147
	v_add_f32_e32 v144, v139, v144
	v_add_f32_e32 v144, v142, v144
	v_add_f32_e32 v170, v143, v144
	v_or_b32_e32 v144, s78, v164
	v_bfe_u32 v164, v169, 4, 4
	v_or_b32_e32 v169, 16, v169
	v_bfe_u32 v171, v168, 4, 4
	v_or_b32_e32 v168, 16, v168
	v_bfe_u32 v172, v167, 4, 4
	v_or_b32_e32 v167, 16, v167
	v_bfe_u32 v173, v166, 4, 4
	v_or_b32_e32 v166, 16, v166
	v_add_u32_e32 v164, v164, v163
	v_add_u32_e32 v169, v169, v163
	v_add_u32_e32 v171, v171, v163
	v_add_u32_e32 v168, v168, v163
	v_add_u32_e32 v172, v172, v163
	v_add_u32_e32 v167, v167, v163
	v_add_u32_e32 v173, v173, v163
	v_add_u32_e32 v166, v166, v163
	v_and_b32_e32 v164, 31, v164
	v_and_b32_e32 v169, 31, v169
	v_and_b32_e32 v171, 31, v171
	v_and_b32_e32 v168, 31, v168
	v_and_b32_e32 v172, 31, v172
	v_and_b32_e32 v167, 31, v167
	v_and_b32_e32 v173, 31, v173
	v_and_b32_e32 v166, 31, v166
	v_lshl_add_u32 v164, v164, 2, v165
	v_lshl_add_u32 v169, v169, 2, v165
	v_lshl_add_u32 v171, v171, 2, v165
	v_lshl_add_u32 v168, v168, 2, v165
	v_lshl_add_u32 v172, v172, 2, v165
	v_lshl_add_u32 v167, v167, 2, v165
	v_lshl_add_u32 v173, v173, 2, v165
	v_lshl_add_u32 v166, v166, 2, v165
	ds_read_b32 v164, v164
	ds_read_b32 v169, v169
	ds_read_b32 v171, v171
	ds_read_b32 v168, v168
	ds_read_b32 v172, v172
	ds_read_b32 v167, v167
	ds_read_b32 v173, v173
	ds_read_b32 v166, v166
	s_waitcnt lgkmcnt(6)
	v_and_b32_e32 v169, 0x7f, v169
	v_lshlrev_b32_e32 v164, 7, v164
	v_and_or_b32 v164, v164, s40, v169
	s_waitcnt lgkmcnt(4)
	v_and_b32_e32 v168, 0x7f, v168
	v_lshlrev_b32_e32 v169, 7, v171
	v_and_or_b32 v168, v169, s40, v168
	s_waitcnt lgkmcnt(2)
	v_and_b32_e32 v167, 0x7f, v167
	v_lshlrev_b32_e32 v169, 7, v172
	v_and_or_b32 v167, v169, s40, v167
	s_waitcnt lgkmcnt(0)
; DI void gemm256_tile(const Params& p, int mode, int layer, const u16* R, const u16* Cc, int brow, int bcol, lchar* shm, int tid_in, int wid) {
;     ...
;       unsigned eid[16];
; #pragma unroll
;       for (int k = 0; k < 16; ++k) {
;         const unsigned code = __float_as_uint(v[k]) & 255u;
;         const unsigned i1 = LL[tok * 32 + (((code >> 4) + tok) & 31)] & 127u, i2 = LL[tok * 32 + ((16 + (code & 15u) + tok) & 31)] & 127u;
;         eid[k] = i1 * 128u + i2;
;       }
	v_and_b32_e32 v166, 0x7f, v166
	v_lshlrev_b32_e32 v169, 7, v173
	v_and_or_b32 v166, v169, s40, v166
	v_bfe_u32 v169, v151, 4, 4
	v_or_b32_e32 v151, 16, v151
	v_bfe_u32 v171, v150, 4, 4
	v_or_b32_e32 v150, 16, v150
	v_bfe_u32 v172, v149, 4, 4
	v_or_b32_e32 v149, 16, v149
	v_bfe_u32 v173, v148, 4, 4
	v_or_b32_e32 v148, 16, v148
	v_add_u32_e32 v169, v169, v163
	v_add_u32_e32 v151, v151, v163
	v_add_u32_e32 v171, v171, v163
	v_add_u32_e32 v150, v150, v163
	v_add_u32_e32 v172, v172, v163
	v_add_u32_e32 v149, v149, v163
	v_add_u32_e32 v173, v173, v163
	v_add_u32_e32 v148, v148, v163
	v_and_b32_e32 v169, 31, v169
	v_and_b32_e32 v151, 31, v151
	v_and_b32_e32 v171, 31, v171
	v_and_b32_e32 v150, 31, v150
	v_and_b32_e32 v172, 31, v172
	v_and_b32_e32 v149, 31, v149
	v_and_b32_e32 v173, 31, v173
	v_and_b32_e32 v148, 31, v148
	v_lshl_add_u32 v169, v169, 2, v165
	v_lshl_add_u32 v151, v151, 2, v165
	v_lshl_add_u32 v171, v171, 2, v165
	v_lshl_add_u32 v150, v150, 2, v165
	v_lshl_add_u32 v172, v172, 2, v165
	v_lshl_add_u32 v149, v149, 2, v165
	v_lshl_add_u32 v173, v173, 2, v165
	v_lshl_add_u32 v148, v148, 2, v165
	ds_read_b32 v169, v169
	ds_read_b32 v151, v151
	ds_read_b32 v171, v171
	ds_read_b32 v150, v150
	ds_read_b32 v172, v172
	ds_read_b32 v149, v149
	ds_read_b32 v173, v173
	ds_read_b32 v148, v148
	s_waitcnt lgkmcnt(6)
	v_and_b32_e32 v151, 0x7f, v151
	v_lshlrev_b32_e32 v169, 7, v169
	v_and_or_b32 v169, v169, s40, v151
	s_waitcnt lgkmcnt(4)
	v_and_b32_e32 v150, 0x7f, v150
	v_lshlrev_b32_e32 v151, 7, v171
	v_and_or_b32 v171, v151, s40, v150
	s_waitcnt lgkmcnt(2)
	v_and_b32_e32 v149, 0x7f, v149
	v_lshlrev_b32_e32 v150, 7, v172
	v_and_or_b32 v149, v150, s40, v149
	s_waitcnt lgkmcnt(0)
	v_and_b32_e32 v148, 0x7f, v148
	v_lshlrev_b32_e32 v150, 7, v173
	v_and_or_b32 v172, v150, s40, v148
	v_bfe_u32 v148, v159, 4, 4
	v_or_b32_e32 v150, 16, v159
	v_bfe_u32 v151, v158, 4, 4
	v_or_b32_e32 v158, 16, v158
	v_bfe_u32 v159, v155, 4, 4
	v_or_b32_e32 v155, 16, v155
	v_bfe_u32 v173, v152, 4, 4
	v_or_b32_e32 v152, 16, v152
	v_add_u32_e32 v148, v148, v163
	v_add_u32_e32 v150, v150, v163
	v_add_u32_e32 v151, v151, v163
	v_add_u32_e32 v158, v158, v163
	v_add_u32_e32 v159, v159, v163
	v_add_u32_e32 v155, v155, v163
	v_add_u32_e32 v173, v173, v163
	v_add_u32_e32 v152, v152, v163
	v_and_b32_e32 v148, 31, v148
	v_and_b32_e32 v150, 31, v150
	v_and_b32_e32 v151, 31, v151
	v_and_b32_e32 v158, 31, v158
	v_and_b32_e32 v159, 31, v159
	v_and_b32_e32 v155, 31, v155
	v_and_b32_e32 v173, 31, v173
	v_and_b32_e32 v152, 31, v152
	v_lshl_add_u32 v148, v148, 2, v165
	v_lshl_add_u32 v150, v150, 2, v165
	v_lshl_add_u32 v151, v151, 2, v165
	v_lshl_add_u32 v158, v158, 2, v165
	v_lshl_add_u32 v159, v159, 2, v165
	v_lshl_add_u32 v155, v155, 2, v165
	v_lshl_add_u32 v173, v173, 2, v165
	v_lshl_add_u32 v152, v152, 2, v165
	ds_read_b32 v148, v148
	ds_read_b32 v150, v150
	ds_read_b32 v151, v151
	ds_read_b32 v158, v158
	ds_read_b32 v159, v159
	ds_read_b32 v155, v155
	ds_read_b32 v173, v173
	ds_read_b32 v152, v152
	s_waitcnt lgkmcnt(6)
	v_and_b32_e32 v150, 0x7f, v150
	v_lshlrev_b32_e32 v148, 7, v148
	v_and_or_b32 v174, v148, s40, v150
	s_waitcnt lgkmcnt(4)
	v_and_b32_e32 v148, 0x7f, v158
	v_lshlrev_b32_e32 v150, 7, v151
	v_and_or_b32 v158, v150, s40, v148
	s_waitcnt lgkmcnt(2)
	v_and_b32_e32 v148, 0x7f, v155
	v_lshlrev_b32_e32 v150, 7, v159
	v_and_or_b32 v155, v150, s40, v148
	s_waitcnt lgkmcnt(0)
; DI void gemm256_tile(const Params& p, int mode, int layer, const u16* R, const u16* Cc, int brow, int bcol, lchar* shm, int tid_in, int wid) {
;     ...
;       const float inv = 1.0f / sum;
;       const int hd = brow >> 8;
;       u16* di = W_IDX(p) + (size_t)(bcol + tok) * 128 + hd * 16;
;       float* dg = W_G(p) + (size_t)(bcol + tok) * 128 + hd * 16;
;       unsigned eid[16];
; #pragma unroll
;       for (int k = 0; k < 16; ++k) {
;         const unsigned code = __float_as_uint(v[k]) & 255u;
;         const unsigned i1 = LL[tok * 32 + (((code >> 4) + tok) & 31)] & 127u, i2 = LL[tok * 32 + ((16 + (code & 15u) + tok) & 31)] & 127u;
;         eid[k] = i1 * 128u + i2;
;       }
; #pragma unroll
;       for (int q = 0; q < 4; ++q) *(f32x4*)(dg + 4 * q) = (f32x4){e[4 * q] * inv, e[4 * q + 1] * inv, e[4 * q + 2] * inv, e[4 * q + 3] * inv};
; #pragma unroll
;       for (int q = 0; q < 2; ++q)
;         *(u32x4*)(di + 8 * q) = (u32x4){eid[8 * q] | (eid[8 * q + 1] << 16), eid[8 * q + 2] | (eid[8 * q + 3] << 16), eid[8 * q + 4] | (eid[8 * q + 5] << 16), eid[8 * q + 6] | (eid[8 * q + 7] << 16)};
	v_and_b32_e32 v148, 0x7f, v152
	v_lshlrev_b32_e32 v150, 7, v173
	v_and_or_b32 v159, v150, s40, v148
	v_bfe_u32 v148, v154, 4, 4
	v_or_b32_e32 v150, 16, v154
	v_bfe_u32 v151, v153, 4, 4
	v_or_b32_e32 v152, 16, v153
	v_bfe_u32 v153, v156, 4, 4
	v_or_b32_e32 v154, 16, v156
	v_bfe_u32 v156, v157, 4, 4
	v_or_b32_e32 v157, 16, v157
	v_add_u32_e32 v148, v148, v163
	v_add_u32_e32 v150, v150, v163
	v_add_u32_e32 v151, v151, v163
	v_add_u32_e32 v152, v152, v163
	v_add_u32_e32 v153, v153, v163
	v_add_u32_e32 v154, v154, v163
	v_add_u32_e32 v156, v156, v163
	v_add_u32_e32 v157, v157, v163
	v_and_b32_e32 v148, 31, v148
	v_and_b32_e32 v150, 31, v150
	v_and_b32_e32 v151, 31, v151
	v_and_b32_e32 v152, 31, v152
	v_and_b32_e32 v153, 31, v153
	v_and_b32_e32 v154, 31, v154
	v_and_b32_e32 v156, 31, v156
	v_and_b32_e32 v157, 31, v157
	v_lshl_add_u32 v148, v148, 2, v165
	v_lshl_add_u32 v150, v150, 2, v165
	v_lshl_add_u32 v151, v151, 2, v165
	v_lshl_add_u32 v152, v152, 2, v165
	v_lshl_add_u32 v153, v153, 2, v165
	v_lshl_add_u32 v154, v154, 2, v165
	v_lshl_add_u32 v156, v156, 2, v165
	v_lshl_add_u32 v157, v157, 2, v165
	ds_read_b32 v148, v148
	ds_read_b32 v150, v150
	ds_read_b32 v151, v151
	ds_read_b32 v152, v152
	ds_read_b32 v153, v153
	ds_read_b32 v154, v154
	ds_read_b32 v156, v156
	ds_read_b32 v157, v157
	s_waitcnt lgkmcnt(6)
	v_and_b32_e32 v150, 0x7f, v150
	v_lshlrev_b32_e32 v148, 7, v148
	v_ashrrev_i32_e32 v145, 31, v144
	v_readlane_b32 s4, v255, 30
	v_and_or_b32 v163, v148, s40, v150
	s_waitcnt lgkmcnt(4)
	v_and_b32_e32 v148, 0x7f, v152
	v_lshlrev_b32_e32 v150, 7, v151
	v_lshlrev_b64 v[146:147], 9, v[144:145]
	v_readlane_b32 s5, v255, 31
	v_and_or_b32 v165, v150, s40, v148
	s_waitcnt lgkmcnt(2)
	v_and_b32_e32 v148, 0x7f, v154
	v_lshlrev_b32_e32 v150, 7, v153
	v_lshl_add_u64 v[146:147], s[4:5], 0, v[146:147]
	v_and_or_b32 v154, v150, s40, v148
	v_div_scale_f32 v148, s[4:5], v170, v170, 1.0
	v_rcp_f32_e32 v150, v148
	s_waitcnt lgkmcnt(0)
	v_and_b32_e32 v151, 0x7f, v157
	v_lshlrev_b32_e32 v152, 7, v156
	v_and_or_b32 v156, v152, s40, v151
	v_fma_f32 v151, -v148, v150, 1.0
	v_fmac_f32_e32 v150, v151, v150
	v_div_scale_f32 v151, vcc, 1.0, v170, 1.0
	v_mul_f32_e32 v152, v151, v150
	v_fma_f32 v153, -v148, v152, v151
	v_fmac_f32_e32 v152, v153, v150
	v_fma_f32 v148, -v148, v152, v151
	s_lshl_b32 s0, s13, 4
	v_div_fmas_f32 v148, v148, v150, v152
	s_ashr_i32 s1, s0, 31
	v_div_fixup_f32 v148, v148, v170, 1.0
	v_lshlrev_b64 v[144:145], 8, v[144:145]
	v_lshl_add_u64 v[152:153], s[0:1], 2, v[146:147]
	v_pk_mul_f32 v[146:147], v[132:133], v[148:149] op_sel_hi:[1,0]
	v_pk_mul_f32 v[132:133], v[136:137], v[148:149] op_sel_hi:[1,0]
	v_pk_mul_f32 v[130:131], v[130:131], v[148:149] op_sel_hi:[1,0]
	v_lshl_add_u64 v[150:151], s[66:67], 0, v[144:145]
	v_pk_mul_f32 v[144:145], v[128:129], v[148:149] op_sel_hi:[1,0]
	global_store_dwordx4 v[152:153], v[130:133], off offset:16
	v_pk_mul_f32 v[128:129], v[134:135], v[148:149] op_sel_hi:[1,0]
	global_store_dwordx4 v[152:153], v[144:147], off
	v_pk_mul_f32 v[130:131], v[140:141], v[148:149] op_sel_hi:[1,0]
	global_store_dwordx4 v[152:153], v[128:131], off offset:32
	v_lshl_add_u64 v[132:133], s[0:1], 1, v[150:151]
	s_nop 0
	v_pk_mul_f32 v[130:131], v[142:143], v[148:149] op_sel_hi:[1,0]
	v_pk_mul_f32 v[128:129], v[138:139], v[148:149] op_sel_hi:[1,0]
	global_store_dwordx4 v[152:153], v[128:131], off offset:48
	s_nop 1
	v_lshl_or_b32 v128, v168, 16, v164
	v_lshl_or_b32 v129, v166, 16, v167
	v_lshl_or_b32 v130, v171, 16, v169
	v_lshl_or_b32 v131, v172, 16, v149
	global_store_dwordx4 v[132:133], v[128:131], off
	s_nop 1
	v_lshl_or_b32 v128, v158, 16, v174
	v_lshl_or_b32 v129, v159, 16, v155
	v_lshl_or_b32 v130, v165, 16, v163
	v_lshl_or_b32 v131, v156, 16, v154
	global_store_dwordx4 v[132:133], v[128:131], off offset:16
